# mixer-B attention uses the relative-score scheme of mixers A/C: B query columns pre-scaled by 0.125*log2e in the GEMM1 epilogue (bf16 rounding of q*c as A/C do), QK accumulators start from -m, no per-
# speedup vs baseline: 1.0182x; 1.0182x over previous
; __device__ __forceinline__ void phase_gemm1(const Params& p, int layer, LAS unsigned char* lds) {
;     ...
;                         if (col0 < 512 || (col0 >= 3328 && col0 < 3840)) {
; #pragma unroll
;                             for (int m = 0; m < 4; m++)
; #pragma unroll
;                                 for (int j = 0; j < 4; j++) v[m][j] *= 0.125f * LOG2E;
;                         }
.LBB0_251:
	s_or_b64 exec, exec, s[10:11]
	s_add_i32 s10, s66, 0xfffff300
	s_cmpk_lt_u32 s10, 0x200
	s_cselect_b64 s[10:11], -1, 0
	s_or_b64 s[12:13], s[54:55], s[10:11]
	s_add_i32 s98, s66, 0xfffffb00
	s_cmpk_lt_u32 s98, 0x200
	s_cselect_b64 s[98:99], -1, 0
	s_or_b64 s[12:13], s[12:13], s[98:99]
	v_cndmask_b32_e64 v0, 0, 1, s[12:13]
	v_cmp_ne_u32_e64 s[10:11], 1, v0
	s_andn2_b64 vcc, exec, s[12:13]
	s_cbranch_vccnz .LBB0_253
	v_pk_mul_f32 v[126:127], v[126:127], s[28:29] op_sel_hi:[1,0]
	v_pk_mul_f32 v[128:129], v[128:129], s[28:29] op_sel_hi:[1,0]
	v_pk_mul_f32 v[122:123], v[122:123], s[28:29] op_sel_hi:[1,0]
	v_pk_mul_f32 v[124:125], v[124:125], s[28:29] op_sel_hi:[1,0]
	v_pk_mul_f32 v[118:119], v[118:119], s[28:29] op_sel_hi:[1,0]
	v_pk_mul_f32 v[120:121], v[120:121], s[28:29] op_sel_hi:[1,0]
	v_pk_mul_f32 v[114:115], v[114:115], s[28:29] op_sel_hi:[1,0]
	v_pk_mul_f32 v[116:117], v[116:117], s[28:29] op_sel_hi:[1,0]

; __device__ __forceinline__ void phase_gemm1(const Params& p, int layer, LAS unsigned char* lds) {
;     ...
;                         if (col0 < 512 || (col0 >= 3328 && col0 < 3840)) {
; #pragma unroll
;                             for (int m = 0; m < 4; m++)
; #pragma unroll
;                                 for (int j = 0; j < 4; j++) v[m][j] *= 0.125f * LOG2E;
;                         }
.LBB0_324:
	s_or_b64 exec, exec, s[0:1]
	s_add_i32 s0, s66, 0xfffff300
	s_cmpk_lt_u32 s0, 0x200
	s_cselect_b64 s[0:1], -1, 0
	s_or_b64 s[0:1], s[54:55], s[0:1]
	s_add_i32 s98, s66, 0xfffffb00
	s_cmpk_lt_u32 s98, 0x200
	s_cselect_b64 s[98:99], -1, 0
	s_or_b64 s[0:1], s[0:1], s[98:99]
	v_cndmask_b32_e64 v67, 0, 1, s[0:1]
	v_cmp_ne_u32_e64 s[12:13], 1, v67
	s_andn2_b64 vcc, exec, s[0:1]
	s_cbranch_vccnz .LBB0_326
	v_pk_mul_f32 v[62:63], v[62:63], s[28:29] op_sel_hi:[1,0]
	v_pk_mul_f32 v[64:65], v[64:65], s[28:29] op_sel_hi:[1,0]
	v_pk_mul_f32 v[58:59], v[58:59], s[28:29] op_sel_hi:[1,0]
	v_pk_mul_f32 v[60:61], v[60:61], s[28:29] op_sel_hi:[1,0]
	v_pk_mul_f32 v[54:55], v[54:55], s[28:29] op_sel_hi:[1,0]
	v_pk_mul_f32 v[56:57], v[56:57], s[28:29] op_sel_hi:[1,0]
	v_pk_mul_f32 v[50:51], v[50:51], s[28:29] op_sel_hi:[1,0]
	v_pk_mul_f32 v[52:53], v[52:53], s[28:29] op_sel_hi:[1,0]

;     __device__ __forceinline__ bf16_t* PROJ() const { return (bf16_t*)(ws + OFF_PROJ); }
; template <bool DIFF>
; __device__ __forceinline__ void attn_unit(const Params& p, int layer, int mode, int bl, int hidx, int qblk, bool isctx, unsigned char* lds) {
;     ...
;     const bf16_t* kp = p.PROJ() + (size_t)(bl * TT) * INW + kcol;
;     const int lr = tid >> 3, lc = tid & 7;
;     u32x4 kr[NKM], vr[DV / 64];
;     bf16x8 qf[4];
;     {
;         unsigned char* qreg = lds + 73728 + wave * 4608;
;         const int tqb = tq - l31;
; #pragma unroll
;         for (int i = 0; i < 4; i++) {
;             const int c = lane + 64 * i, row = c >> 3, ch = c & 7;
;             *(u32x4*)(qreg + row * LROW + ch * 16) = *(const u32x4*)(p.PROJ() + (size_t)(tqb + row) * INW + qcol + ch * 8);
;         }
; #pragma unroll
;         for (int kk = 0; kk < 4; kk++) qf[kk] = *(const bf16x8*)(qreg + l31 * LROW + kk * 32 + hh * 16);
;     }
;     f32x16 O[DV / 32];
; #pragma unroll
;     for (int dt = 0; dt < DV / 32; dt++)
; #pragma unroll
;         for (int r = 0; r < 16; r++) O[dt][r] = 0.f;
;     float m = DIFF ? -1e30f : 0.f, l = 0.f;
;     f32x16 NEGM;
; #pragma unroll
;     for (int r = 0; r < 16; r++) NEGM[r] = 0.f;
;     {
;         const int t0 = 0;
; #pragma unroll
;         for (int i = 0; i < NKM; i++) kr[i] = *(const u32x4*)(kp + (size_t)(t0 + lr) * INW + i * 64 + lc * 8);
; #pragma unroll
;         for (int i = 0; i < DV / 64; i++) vr[i] = *(const u32x4*)(vt + (size_t)(lr + i * 64) * TT + t0 + lc * 8);
;     }
;     __syncthreads();
;     {
;         unsigned char* wb = lds + lr * LROW + lc * 16;
; #pragma unroll
;         for (int i = 0; i < NKM; i++) *(u32x4*)(wb + i * 9216) = kr[i];
; #pragma unroll
;         for (int i = 0; i < DV / 64; i++) *(u32x4*)(wb + KBYTES + i * 64 * LROW) = vr[i];
;     }
;     __syncthreads();
.LBB0_496:
	s_and_b64 vcc, exec, s[0:1]
	s_cbranch_vccz .LBB0_435
	v_mov_b32_e32 v34, v168
	s_lshl_b32 s0, s57, 2
	s_or_b32 s0, s0, s56
	v_readfirstlane_b32 s14, v34
	s_ashr_i32 s10, s14, 6
	s_mul_hi_i32 s30, s0, 0x90000
	s_mul_i32 s31, s0, 0x90000
	s_ashr_i32 s0, s14, 2
	s_and_b32 s13, s10, 1
	s_lshl_b32 s11, s56, 7
	s_lshl_b32 s12, s55, 7
	s_and_b32 s16, s0, 0xffffffe0
	s_and_b64 s[0:1], s[8:9], exec
	s_cselect_b32 s15, 0, 0x100
	s_add_u32 s0, s20, s67
	s_addc_u32 s1, s21, s74
	s_lshl_b32 s24, s56, 8
	s_add_u32 s0, s0, s24
	s_addc_u32 s1, s1, 0
	s_add_u32 s0, s0, 0xc13ef00
	s_addc_u32 s1, s1, 0
	s_add_i32 s12, s12, s15
	s_add_i32 s12, s12, s66
	s_mul_i32 s17, s10, 0x1200
	s_add_i32 s12, s12, s16
	v_bfe_u32 v35, v34, 3, 3
	s_add_i32 s17, s17, 0
	v_or_b32_e32 v14, s12, v35
	v_mov_b64_e32 v[10:11], s[60:61]
	s_add_i32 s42, s17, 0x12000
	v_mad_i64_i32 v[2:3], s[16:17], v14, s80, v[10:11]
	s_lshl_b32 s16, s13, 7
	v_or_b32_e32 v4, 8, v14
	v_or_b32_e32 v12, 16, v14
	v_or_b32_e32 v14, 24, v14
	v_lshlrev_b32_e32 v0, 4, v34
	s_or_b32 s24, s16, s24
	v_mad_i64_i32 v[4:5], s[16:17], v4, s80, v[10:11]
	v_mad_i64_i32 v[12:13], s[16:17], v12, s80, v[10:11]
	v_mad_i64_i32 v[10:11], s[16:17], v14, s80, v[10:11]
	v_and_b32_e32 v0, 0x70, v0
	v_lshl_add_u64 v[2:3], v[2:3], 0, s[24:25]
	v_lshl_add_u64 v[4:5], v[4:5], 0, s[24:25]
	v_lshl_add_u64 v[12:13], v[12:13], 0, s[24:25]
	v_lshl_add_u64 v[10:11], v[10:11], 0, s[24:25]
	v_lshl_add_u64 v[2:3], v[2:3], 0, v[0:1]
	v_lshl_add_u64 v[6:7], v[4:5], 0, v[0:1]
	v_lshl_add_u64 v[12:13], v[12:13], 0, v[0:1]
	v_lshl_add_u64 v[14:15], v[10:11], 0, v[0:1]
	global_load_dwordx4 v[2:5], v[2:3], off offset:2560
	s_nop 0
	global_load_dwordx4 v[6:9], v[6:7], off offset:2560
	s_nop 0
	global_load_dwordx4 v[10:13], v[12:13], off offset:2560
	s_nop 0
	global_load_dwordx4 v[14:17], v[14:15], off offset:2560
	s_add_u32 s16, s23, s31
	v_readlane_b32 s17, v254, 20
	s_addc_u32 s17, s17, s30
	v_ashrrev_i32_e32 v146, 3, v34
	v_mov_b64_e32 v[18:19], s[0:1]
	v_mad_i64_i32 v[18:19], s[30:31], v146, s80, v[18:19]
	v_lshl_add_u64 v[132:133], s[16:17], 0, v[0:1]
	v_add_u32_e32 v36, 64, v146
	v_lshl_add_u64 v[22:23], v[18:19], 0, v[0:1]
	v_mad_i64_i32 v[26:27], s[16:17], v146, s38, v[132:133]
	v_mad_i64_i32 v[30:31], s[16:17], v36, s38, v[132:133]
	global_load_dwordx4 v[18:21], v[22:23], off
	s_nop 0
	global_load_dwordx4 v[22:25], v[22:23], off offset:128
	s_nop 0
	global_load_dwordx4 v[26:29], v[26:27], off
	s_nop 0
	global_load_dwordx4 v[30:33], v[30:31], off
	v_mad_i64_i32 v[134:135], s[16:17], v146, s38, 0
	v_and_b32_e32 v142, 31, v34
	v_bfe_u32 v143, v34, 5, 1
	v_mul_u32_u24_e32 v34, 0x90, v35
	s_movk_i32 s16, 0x90
	v_mul_u32_u24_e32 v144, 0x90, v142
	v_lshlrev_b32_e32 v191, 4, v143
	v_mul_lo_u32 v35, v146, s16
	v_add3_u32 v34, s42, v0, v34
	v_add3_u32 v147, 0, v35, v0
	v_add3_u32 v35, s42, v144, v191
	v_cmp_lt_i32_e32 vcc, v179, v180
	v_mad_i64_i32 v[136:137], s[16:17], v36, s38, 0
	v_lshl_add_u64 v[140:141], s[0:1], 0, v[0:1]
	s_and_b64 s[0:1], s[8:9], exec
	v_mov_b32_e32 v0, v1
	s_mov_b32 s24, 0
	s_mul_i32 s30, s13, 0x2400
	s_cselect_b32 s0, 3, 35
	v_mov_b32_e32 v148, 0
	v_mov_b32_e32 v234, 0
	v_mov_b32_e32 v235, 0
	v_mov_b32_e32 v236, 0
	v_mov_b32_e32 v237, 0
	v_mov_b32_e32 v238, 0
	v_mov_b32_e32 v239, 0
	v_mov_b32_e32 v240, 0
	v_mov_b32_e32 v241, 0
	v_mov_b32_e32 v242, 0
	v_mov_b32_e32 v243, 0
	v_mov_b32_e32 v244, 0
	v_mov_b32_e32 v245, 0
	v_mov_b32_e32 v246, 0
	v_mov_b32_e32 v247, 0
	v_mov_b32_e32 v248, 0
	v_mov_b32_e32 v249, 0
	v_mov_b32_e32 v145, 0
	s_movk_i32 s1, 0xff40
	s_waitcnt vmcnt(7)
	ds_write_b128 v34, v[2:5]
	s_waitcnt vmcnt(6)
	ds_write_b128 v34, v[6:9] offset:1152
	s_waitcnt vmcnt(5)
	ds_write_b128 v34, v[10:13] offset:2304
	s_waitcnt vmcnt(4)
	ds_write_b128 v34, v[14:17] offset:3456
	ds_read_b128 v[124:127], v35
	ds_read_b128 v[120:123], v35 offset:32
	ds_read_b128 v[116:119], v35 offset:64
	ds_read_b128 v[112:115], v35 offset:96
	v_cndmask_b32_e32 v2, v178, v179, vcc
	v_mov_b32_e32 v14, v1
	v_mov_b32_e32 v15, v1
	s_waitcnt lgkmcnt(0)
	s_barrier
	s_waitcnt vmcnt(3)
	ds_write_b128 v147, v[18:21]
	s_waitcnt vmcnt(2)
	ds_write_b128 v147, v[22:25] offset:9216
	s_waitcnt vmcnt(1)
	ds_write_b128 v147, v[26:29] offset:18432
	s_waitcnt vmcnt(0)
	ds_write_b128 v147, v[30:33] offset:27648
	v_lshlrev_b32_e32 v192, 2, v2
	v_mov_b32_e32 v2, v1
	v_mov_b32_e32 v3, v1
	v_mov_b32_e32 v4, v1
	v_mov_b32_e32 v5, v1
	v_mov_b32_e32 v6, v1
	v_mov_b32_e32 v7, v1
	v_mov_b32_e32 v8, v1
	v_mov_b32_e32 v9, v1
	v_mov_b32_e32 v10, v1
	v_mov_b32_e32 v11, v1
	v_mov_b32_e32 v12, v1
	v_mov_b32_e32 v13, v1
	v_mov_b64_e32 v[30:31], v[14:15]
	v_mov_b64_e32 v[46:47], v[14:15]
	v_mov_b64_e32 v[62:63], v[14:15]
	v_mov_b64_e32 v[78:79], v[14:15]
	v_mov_b64_e32 v[28:29], v[12:13]
	v_mov_b64_e32 v[26:27], v[10:11]
	v_mov_b64_e32 v[24:25], v[8:9]
	v_mov_b64_e32 v[22:23], v[6:7]
	v_mov_b64_e32 v[20:21], v[4:5]
	v_mov_b64_e32 v[18:19], v[2:3]
	v_mov_b64_e32 v[16:17], v[0:1]
	v_mov_b64_e32 v[44:45], v[12:13]
	v_mov_b64_e32 v[42:43], v[10:11]
	v_mov_b64_e32 v[40:41], v[8:9]
	v_mov_b64_e32 v[38:39], v[6:7]
	v_mov_b64_e32 v[36:37], v[4:5]
	v_mov_b64_e32 v[34:35], v[2:3]
	v_mov_b64_e32 v[32:33], v[0:1]
	v_mov_b64_e32 v[60:61], v[12:13]
	v_mov_b64_e32 v[58:59], v[10:11]
	v_mov_b64_e32 v[56:57], v[8:9]
	v_mov_b64_e32 v[54:55], v[6:7]
	v_mov_b64_e32 v[52:53], v[4:5]
	v_mov_b64_e32 v[50:51], v[2:3]
	v_mov_b64_e32 v[48:49], v[0:1]
	v_mov_b64_e32 v[76:77], v[12:13]
	v_mov_b64_e32 v[74:75], v[10:11]
	v_mov_b64_e32 v[72:73], v[8:9]
	v_mov_b64_e32 v[70:71], v[6:7]
	v_mov_b64_e32 v[68:69], v[4:5]
	v_mov_b64_e32 v[66:67], v[2:3]
	v_mov_b64_e32 v[64:65], v[0:1]
	s_waitcnt lgkmcnt(0)
	s_barrier
	s_branch .LBB0_499
; #define MFMA(a, b, c) __builtin_amdgcn_mfma_f32_32x32x16_bf16((a), (b), (c), 0, 0, 0)
; __device__ __forceinline__ unsigned pk2(float lo, float hi) { const f32x2_t f = {lo, hi}; const bf16x2_t b = __builtin_convertvector(f, bf16x2_t); return __builtin_bit_cast(unsigned, b); }
; template <int DV> ...
;     ...
;     float ps = 0.f;
; #pragma unroll
;     for (int sub = 0; sub < 2; sub++)
; #pragma unroll
;         for (int r = 0; r < 16; r++) { S[sub][r] = __builtin_amdgcn_exp2f(S[sub][r]); ps += S[sub][r]; }
;     l += ps;
; #pragma unroll
;     for (int sub = 0; sub < 2; sub++)
; #pragma unroll
;         for (int s = 0; s < 2; s++) {
;             u32x4 cv;
;             cv[0] = pk2(S[sub][8 * s + 0], S[sub][8 * s + 1]); cv[1] = pk2(S[sub][8 * s + 2], S[sub][8 * s + 3]);
;             cv[2] = pk2(S[sub][8 * s + 4], S[sub][8 * s + 5]); cv[3] = pk2(S[sub][8 * s + 6], S[sub][8 * s + 7]);
;             const bf16x8 pb = __builtin_bit_cast(bf16x8, cv);
; #pragma unroll
;             for (int dt = 0; dt < DV / 32; dt++) {
;                 const bf16x8 vf = *(const bf16x8*)(Vl + (dt * 32 + l31) * LROW + (sub * 4 + s * 2 + hh) * 16);
;                 O[dt] = MFMA(vf, pb, O[dt]);
;             }
;         }
; template <bool DIFF>
; __device__ __forceinline__ void attn_unit(const Params& p, int layer, int mode, int bl, int hidx, int qblk, bool isctx, unsigned char* lds) {
;     ...
;         if (more) {
;             unsigned char* wb = lds + ((it + 1) & 1) * BUFB + lr * LROW + lc * 16;
; #pragma unroll
;             for (int i = 0; i < NKM; i++) *(u32x4*)(wb + i * 9216) = kr[i];
; #pragma unroll
;             for (int i = 0; i < DV / 64; i++) *(u32x4*)(wb + KBYTES + i * 64 * LROW) = vr[i];
;         }
;         __syncthreads();
.LBB0_498:
	v_exp_f32_e32 v96, v96
	v_exp_f32_e32 v97, v97
	v_exp_f32_e32 v98, v98
	v_exp_f32_e32 v99, v99
	v_exp_f32_e32 v100, v100
	v_exp_f32_e32 v101, v101
	v_exp_f32_e32 v102, v102
	v_exp_f32_e32 v103, v103
	v_cvt_pk_bf16_f32 v164, v96, v97
	v_cvt_pk_bf16_f32 v165, v98, v99
	v_add_f32_e32 v14, v97, v96
	v_cvt_pk_bf16_f32 v166, v100, v101
	v_add_f32_e32 v14, v98, v14
	v_add_f32_e32 v14, v99, v14
	v_cvt_pk_bf16_f32 v167, v102, v103
	v_add_f32_e32 v14, v100, v14
	v_add_f32_e32 v14, v101, v14
	s_waitcnt lgkmcnt(11)
	v_mfma_f32_32x32x16_bf16 v[64:79], v[226:229], v[164:167], v[64:79]
	ds_read_b128 v[226:229], v193 offset:18528
	v_exp_f32_e32 v104, v104
	v_exp_f32_e32 v105, v105
	v_exp_f32_e32 v106, v106
	v_exp_f32_e32 v107, v107
	s_waitcnt lgkmcnt(11)
	v_mfma_f32_32x32x16_bf16 v[48:63], v[230:233], v[164:167], v[48:63]
	ds_read_b128 v[230:233], v193 offset:23136
	v_exp_f32_e32 v108, v108
	v_exp_f32_e32 v109, v109
	v_exp_f32_e32 v110, v110
	v_exp_f32_e32 v111, v111
	v_add_f32_e32 v14, v102, v14
	s_waitcnt lgkmcnt(11)
	v_mfma_f32_32x32x16_bf16 v[32:47], v[156:159], v[164:167], v[32:47]
	ds_read_b128 v[156:159], v193 offset:27744
	v_add_f32_e32 v14, v103, v14
	v_cvt_pk_bf16_f32 v96, v104, v105
	v_cvt_pk_bf16_f32 v97, v106, v107
	v_add_f32_e32 v14, v104, v14
	s_waitcnt lgkmcnt(11)
	v_mfma_f32_32x32x16_bf16 v[16:31], v[160:163], v[164:167], v[16:31]
	ds_read_b128 v[160:163], v193 offset:32352
	v_add_f32_e32 v14, v105, v14
	v_cvt_pk_bf16_f32 v98, v108, v109
	v_add_f32_e32 v14, v106, v14
	v_cvt_pk_bf16_f32 v99, v110, v111
	v_add_f32_e32 v14, v107, v14
	v_add_f32_e32 v14, v108, v14
	v_add_f32_e32 v14, v109, v14
	s_waitcnt lgkmcnt(11)
	v_mfma_f32_32x32x16_bf16 v[64:79], v[194:197], v[96:99], v[64:79]
	v_exp_f32_e32 v80, v80
	v_exp_f32_e32 v81, v81
	v_exp_f32_e32 v82, v82
	v_exp_f32_e32 v83, v83
	s_waitcnt lgkmcnt(10)
	v_mfma_f32_32x32x16_bf16 v[48:63], v[198:201], v[96:99], v[48:63]
	v_exp_f32_e32 v84, v84
	v_exp_f32_e32 v85, v85
	v_exp_f32_e32 v86, v86
	v_exp_f32_e32 v87, v87
	v_add_f32_e32 v14, v110, v14
	s_waitcnt lgkmcnt(9)
	v_mfma_f32_32x32x16_bf16 v[32:47], v[202:205], v[96:99], v[32:47]
	v_add_f32_e32 v14, v111, v14
	v_cvt_pk_bf16_f32 v100, v80, v81
	v_cvt_pk_bf16_f32 v101, v82, v83
	v_add_f32_e32 v14, v80, v14
	s_waitcnt lgkmcnt(8)
	v_mfma_f32_32x32x16_bf16 v[16:31], v[206:209], v[96:99], v[16:31]
	v_add_f32_e32 v14, v81, v14
	v_cvt_pk_bf16_f32 v102, v84, v85
	v_add_f32_e32 v14, v82, v14
	v_cvt_pk_bf16_f32 v103, v86, v87
	v_add_f32_e32 v14, v83, v14
	v_add_f32_e32 v14, v84, v14
	v_add_f32_e32 v14, v85, v14
	s_waitcnt lgkmcnt(7)
	v_mfma_f32_32x32x16_bf16 v[64:79], v[210:213], v[100:103], v[64:79]
	v_exp_f32_e32 v88, v88
	v_exp_f32_e32 v89, v89
	v_exp_f32_e32 v90, v90
	v_exp_f32_e32 v91, v91
	s_waitcnt lgkmcnt(6)
	v_mfma_f32_32x32x16_bf16 v[48:63], v[214:217], v[100:103], v[48:63]
	v_exp_f32_e32 v92, v92
	v_exp_f32_e32 v93, v93
	v_exp_f32_e32 v94, v94
	v_exp_f32_e32 v95, v95
	v_add_f32_e32 v14, v86, v14
	s_waitcnt lgkmcnt(5)
	v_mfma_f32_32x32x16_bf16 v[32:47], v[218:221], v[100:103], v[32:47]
	v_add_f32_e32 v14, v87, v14
	v_cvt_pk_bf16_f32 v104, v88, v89
	v_cvt_pk_bf16_f32 v105, v90, v91
	v_add_f32_e32 v14, v88, v14
	s_waitcnt lgkmcnt(4)
	v_mfma_f32_32x32x16_bf16 v[16:31], v[222:225], v[100:103], v[16:31]
	v_add_f32_e32 v14, v89, v14
	v_cvt_pk_bf16_f32 v106, v92, v93
	v_add_f32_e32 v14, v90, v14
	v_cvt_pk_bf16_f32 v107, v94, v95
	v_add_f32_e32 v14, v91, v14
	v_add_f32_e32 v14, v92, v14
	v_add_f32_e32 v14, v93, v14
	s_waitcnt lgkmcnt(3)
	v_mfma_f32_32x32x16_bf16 v[64:79], v[226:229], v[104:107], v[64:79]
	v_add_f32_e32 v14, v94, v14
	s_add_i32 s24, s24, 1
	v_add_f32_e32 v14, v95, v14
	s_bitcmp1_b32 s24, 0
	s_cselect_b32 s8, 0x9000, 0
	s_add_i32 s1, s1, 64
	s_waitcnt lgkmcnt(2)
	v_mfma_f32_32x32x16_bf16 v[48:63], v[230:233], v[104:107], v[48:63]
	v_add_f32_e32 v145, v145, v14
	v_add_u32_e32 v0, s8, v147
	s_waitcnt vmcnt(3)
	ds_write_b128 v0, v[2:5]
	s_waitcnt vmcnt(2)
	ds_write_b128 v0, v[6:9] offset:9216
	s_waitcnt vmcnt(1)
	ds_write_b128 v0, v[10:13] offset:18432
	s_waitcnt vmcnt(0)
	ds_write_b128 v0, v[128:131] offset:27648
	s_cmp_eq_u32 s0, s24
	s_waitcnt lgkmcnt(0)
	s_barrier
	v_mfma_f32_32x32x16_bf16 v[32:47], v[156:159], v[104:107], v[32:47]
	v_mfma_f32_32x32x16_bf16 v[16:31], v[160:163], v[104:107], v[16:31]
	s_cbranch_scc1 .LBB0_501
; #define MFMA(a, b, c) __builtin_amdgcn_mfma_f32_32x32x16_bf16((a), (b), (c), 0, 0, 0)
; template <int DV> ...
;     ...
;     f32x16 S[2];
; #pragma unroll
;     for (int sub = 0; sub < 2; sub++) {
;         const bf16x8 kf = *(const bf16x8*)(Kl + (sub * 32 + l31) * LROW + hh * 16);
;         S[sub] = MFMA(kf, qf[0], NEGM);
;     }
; #pragma unroll
;     for (int kk = 1; kk < 4; kk++)
; #pragma unroll
;         for (int sub = 0; sub < 2; sub++) {
;             const bf16x8 kf = *(const bf16x8*)(Kl + (sub * 32 + l31) * LROW + kk * 32 + hh * 16);
;             S[sub] = MFMA(kf, qf[kk], S[sub]);
;         }
;     if (domask) {
; #pragma unroll
;         for (int sub = 0; sub < 2; sub++)
; #pragma unroll
;             for (int r = 0; r < 16; r++) {
;                 const int d = qpos - (kpos0 + sub * 32 + (r & 3) + 8 * (r >> 2) + 4 * hh);
;                 S[sub][r] = (d <= 128 && d >= -128) ? S[sub][r] : -1e30f;
;             }
;     }
;     float mx = S[0][0];
; #pragma unroll
;     for (int sub = 0; sub < 2; sub++)
; #pragma unroll
;         for (int r = 0; r < 16; r++) mx = fmaxf(mx, S[sub][r]);
;     mx = fmaxf(mx, __shfl_xor(mx, 32));
;     if (first || __any(mx > THR)) {
;         const float d = first ? mx : fmaxf(mx, 0.f);
;         const float alpha = __builtin_amdgcn_exp2f(-d);
;         m += d; l *= alpha;
; #pragma unroll
;         for (int dt = 0; dt < DV / 32; dt++)
; #pragma unroll
;             for (int r = 0; r < 16; r++) O[dt][r] *= alpha;
; #pragma unroll
;         for (int r = 0; r < 16; r++) NEGM[r] -= d;
; #pragma unroll
;         for (int sub = 0; sub < 2; sub++)
; #pragma unroll
;             for (int r = 0; r < 16; r++) S[sub][r] -= d;
;     }
; template <bool DIFF>
; __device__ __forceinline__ void attn_unit(const Params& p, int layer, int mode, int bl, int hidx, int qblk, bool isctx, unsigned char* lds) {
;     ...
;         if (more) {
;             const int t0 = (it + 1 < 4) ? (it + 1) * 64 : start2 + (it + 1 - 4) * 64;
; #pragma unroll
;             for (int i = 0; i < NKM; i++) kr[i] = *(const u32x4*)(kp + (size_t)(t0 + lr) * INW + i * 64 + lc * 8);
; #pragma unroll
;             for (int i = 0; i < DV / 64; i++) vr[i] = *(const u32x4*)(vt + (size_t)(lr + i * 64) * TT + t0 + lc * 8);
;         }
;         const int tcur = (it < 4) ? it * 64 : start2 + (it - 4) * 64;
.LBB0_499:
	s_bitcmp1_b32 s24, 0
	s_cselect_b32 s8, 0x9000, 0
	s_add_i32 s8, s8, 0
	s_add_i32 s9, s1, 0x100
	s_add_i32 s16, s15, s1
	s_cmp_lt_u32 s24, 3
	s_cselect_b32 s16, s9, s16
	s_ashr_i32 s17, s16, 31
	v_add_u32_e32 v0, s16, v146
	v_lshl_add_u64 v[14:15], s[16:17], 1, v[132:133]
	s_add_i32 s9, s8, s30
	v_mad_i64_i32 v[6:7], s[42:43], v0, s80, v[140:141]
	v_lshl_add_u64 v[10:11], v[14:15], 0, v[134:135]
	v_lshl_add_u64 v[14:15], v[14:15], 0, v[136:137]
	v_add3_u32 v0, s9, v191, v144
	global_load_dwordx4 v[2:5], v[6:7], off
	s_nop 0
	global_load_dwordx4 v[6:9], v[6:7], off offset:128
	s_nop 0
	global_load_dwordx4 v[10:13], v[10:11], off
	s_nop 0
	global_load_dwordx4 v[128:131], v[14:15], off
	v_add3_u32 v193, s8, v191, v144
	ds_read_b128 v[194:197], v0
	ds_read_b128 v[198:201], v0 offset:4608
	ds_read_b128 v[202:205], v0 offset:32
	ds_read_b128 v[206:209], v0 offset:4640
	ds_read_b128 v[210:213], v0 offset:64
	ds_read_b128 v[214:217], v0 offset:4672
	ds_read_b128 v[218:221], v0 offset:96
	ds_read_b128 v[222:225], v0 offset:4704
	s_waitcnt lgkmcnt(7)
	v_mfma_f32_32x32x16_bf16 v[96:111], v[194:197], v[124:127], v[234:249]
	s_waitcnt lgkmcnt(6)
	v_mfma_f32_32x32x16_bf16 v[80:95], v[198:201], v[124:127], v[234:249]
	ds_read_b128 v[226:229], v193 offset:18432
	ds_read_b128 v[230:233], v193 offset:23040
	ds_read_b128 v[156:159], v193 offset:27648
	ds_read_b128 v[160:163], v193 offset:32256
	s_waitcnt lgkmcnt(9)
	v_mfma_f32_32x32x16_bf16 v[96:111], v[202:205], v[120:123], v[96:111]
	s_waitcnt lgkmcnt(8)
	v_mfma_f32_32x32x16_bf16 v[80:95], v[206:209], v[120:123], v[80:95]
	ds_read_b128 v[194:197], v193 offset:18464
	ds_read_b128 v[198:201], v193 offset:23072
	ds_read_b128 v[202:205], v193 offset:27680
	ds_read_b128 v[206:209], v193 offset:32288
	s_waitcnt lgkmcnt(11)
	v_mfma_f32_32x32x16_bf16 v[96:111], v[210:213], v[116:119], v[96:111]
	s_waitcnt lgkmcnt(10)
	v_mfma_f32_32x32x16_bf16 v[80:95], v[214:217], v[116:119], v[80:95]
	s_waitcnt lgkmcnt(9)
	v_mfma_f32_32x32x16_bf16 v[96:111], v[218:221], v[112:115], v[96:111]
	s_waitcnt lgkmcnt(8)
	v_mfma_f32_32x32x16_bf16 v[80:95], v[222:225], v[112:115], v[80:95]
	ds_read_b128 v[210:213], v193 offset:18496
	ds_read_b128 v[214:217], v193 offset:23104
	ds_read_b128 v[218:221], v193 offset:27712
	ds_read_b128 v[222:225], v193 offset:32320
	s_nop 5
	v_max3_f32 v0, v96, v97, v98
	v_max3_f32 v0, v0, v99, v100
	v_max3_f32 v0, v0, v101, v102
	v_max3_f32 v0, v0, v103, v104
	v_max3_f32 v14, v80, v81, v82
	v_max3_f32 v0, v0, v105, v106
	v_max3_f32 v14, v14, v83, v84
	v_max3_f32 v0, v0, v107, v108
	v_max3_f32 v14, v14, v85, v86
	v_max3_f32 v0, v0, v109, v110
	v_max3_f32 v14, v14, v87, v88
	v_max3_f32 v14, v14, v89, v90
	v_max3_f32 v14, v14, v91, v92
	v_max3_f32 v14, v14, v93, v94
	v_max3_f32 v0, v0, v111, v95
	v_max_f32_e32 v0, v0, v14
	v_mov_b32_e32 v14, v0
	s_nop 1
	v_permlane32_swap_b32_e32 v0, v14
	v_max_f32_e32 v0, v0, v14
	s_cmp_eq_u32 s24, 0
	s_cbranch_scc1 .Lb_resc_first
	v_mov_b32_e32 v14, 0x41000000
	v_cmp_gt_f32_e32 vcc, v0, v14
	s_cbranch_vccz .LBB0_498
	v_max_f32_e32 v0, 0, v0
.Lb_resc_first:
	v_exp_f32_e64 v14, -v0
	v_add_f32_e32 v148, v148, v0
	s_nop 0
	v_mul_f32_e32 v145, v145, v14
	v_pk_mul_f32 v[78:79], v[78:79], v[14:15] op_sel_hi:[1,0]
	v_pk_mul_f32 v[76:77], v[76:77], v[14:15] op_sel_hi:[1,0]
	v_pk_mul_f32 v[74:75], v[74:75], v[14:15] op_sel_hi:[1,0]
	v_pk_mul_f32 v[72:73], v[72:73], v[14:15] op_sel_hi:[1,0]
	v_pk_mul_f32 v[70:71], v[70:71], v[14:15] op_sel_hi:[1,0]
	v_pk_mul_f32 v[68:69], v[68:69], v[14:15] op_sel_hi:[1,0]
	v_pk_mul_f32 v[66:67], v[66:67], v[14:15] op_sel_hi:[1,0]
	v_pk_mul_f32 v[64:65], v[64:65], v[14:15] op_sel_hi:[1,0]
	v_pk_mul_f32 v[62:63], v[62:63], v[14:15] op_sel_hi:[1,0]
	v_pk_mul_f32 v[60:61], v[60:61], v[14:15] op_sel_hi:[1,0]
	v_pk_mul_f32 v[58:59], v[58:59], v[14:15] op_sel_hi:[1,0]
	v_pk_mul_f32 v[56:57], v[56:57], v[14:15] op_sel_hi:[1,0]
	v_pk_mul_f32 v[54:55], v[54:55], v[14:15] op_sel_hi:[1,0]
	v_pk_mul_f32 v[52:53], v[52:53], v[14:15] op_sel_hi:[1,0]
	v_pk_mul_f32 v[50:51], v[50:51], v[14:15] op_sel_hi:[1,0]
	v_pk_mul_f32 v[48:49], v[48:49], v[14:15] op_sel_hi:[1,0]
	v_pk_mul_f32 v[46:47], v[46:47], v[14:15] op_sel_hi:[1,0]
	v_pk_mul_f32 v[44:45], v[44:45], v[14:15] op_sel_hi:[1,0]
	v_pk_mul_f32 v[42:43], v[42:43], v[14:15] op_sel_hi:[1,0]
	v_pk_mul_f32 v[40:41], v[40:41], v[14:15] op_sel_hi:[1,0]
	v_pk_mul_f32 v[38:39], v[38:39], v[14:15] op_sel_hi:[1,0]
	v_pk_mul_f32 v[36:37], v[36:37], v[14:15] op_sel_hi:[1,0]
	v_pk_mul_f32 v[34:35], v[34:35], v[14:15] op_sel_hi:[1,0]
	v_pk_mul_f32 v[32:33], v[32:33], v[14:15] op_sel_hi:[1,0]
	v_pk_mul_f32 v[30:31], v[30:31], v[14:15] op_sel_hi:[1,0]
	v_pk_mul_f32 v[28:29], v[28:29], v[14:15] op_sel_hi:[1,0]
	v_pk_mul_f32 v[26:27], v[26:27], v[14:15] op_sel_hi:[1,0]
	v_pk_mul_f32 v[24:25], v[24:25], v[14:15] op_sel_hi:[1,0]
	v_pk_mul_f32 v[22:23], v[22:23], v[14:15] op_sel_hi:[1,0]
	v_pk_mul_f32 v[20:21], v[20:21], v[14:15] op_sel_hi:[1,0]
	v_pk_mul_f32 v[18:19], v[18:19], v[14:15] op_sel_hi:[1,0]
	v_pk_mul_f32 v[16:17], v[16:17], v[14:15] op_sel_hi:[1,0]
	v_sub_f32_e32 v234, v234, v0
	v_sub_f32_e32 v235, v235, v0
	v_sub_f32_e32 v236, v236, v0
	v_sub_f32_e32 v237, v237, v0
	v_sub_f32_e32 v238, v238, v0
	v_sub_f32_e32 v239, v239, v0
	v_sub_f32_e32 v240, v240, v0
	v_sub_f32_e32 v241, v241, v0
	v_sub_f32_e32 v242, v242, v0
	v_sub_f32_e32 v243, v243, v0
	v_sub_f32_e32 v244, v244, v0
	v_sub_f32_e32 v245, v245, v0
	v_sub_f32_e32 v246, v246, v0
	v_sub_f32_e32 v247, v247, v0
	v_sub_f32_e32 v248, v248, v0
	v_sub_f32_e32 v249, v249, v0
	v_sub_f32_e32 v96, v96, v0
	v_sub_f32_e32 v97, v97, v0
	v_sub_f32_e32 v98, v98, v0
	v_sub_f32_e32 v99, v99, v0
	v_sub_f32_e32 v100, v100, v0
	v_sub_f32_e32 v101, v101, v0
	v_sub_f32_e32 v102, v102, v0
	v_sub_f32_e32 v103, v103, v0
	v_sub_f32_e32 v104, v104, v0
	v_sub_f32_e32 v105, v105, v0
	v_sub_f32_e32 v106, v106, v0
	v_sub_f32_e32 v107, v107, v0
	v_sub_f32_e32 v108, v108, v0
	v_sub_f32_e32 v109, v109, v0
	v_sub_f32_e32 v110, v110, v0
	v_sub_f32_e32 v111, v111, v0
	v_sub_f32_e32 v80, v80, v0
	v_sub_f32_e32 v81, v81, v0
	v_sub_f32_e32 v82, v82, v0
	v_sub_f32_e32 v83, v83, v0
	v_sub_f32_e32 v84, v84, v0
	v_sub_f32_e32 v85, v85, v0
	v_sub_f32_e32 v86, v86, v0
	v_sub_f32_e32 v87, v87, v0
	v_sub_f32_e32 v88, v88, v0
	v_sub_f32_e32 v89, v89, v0
	v_sub_f32_e32 v90, v90, v0
	v_sub_f32_e32 v91, v91, v0
	v_sub_f32_e32 v92, v92, v0
	v_sub_f32_e32 v93, v93, v0
	v_sub_f32_e32 v94, v94, v0
	v_sub_f32_e32 v95, v95, v0
	s_branch .LBB0_498
; #define MFMA(a, b, c) __builtin_amdgcn_mfma_f32_32x32x16_bf16((a), (b), (c), 0, 0, 0)
; template <int DV>
; __device__ __forceinline__ void attn_tile(const unsigned char* Kl, const unsigned char* Vl, const bf16x8 (&qf)[4], f32x16 (&O)[DV / 32], float& m, float& l,
;                                           int l31, int hh, bool domask, int qpos, int kpos0) {
;     ...
;     f32x16 S[2];
; #pragma unroll
;     for (int sub = 0; sub < 2; sub++)
; #pragma unroll
;         for (int r = 0; r < 16; r++) S[sub][r] = 0.f;
; #pragma unroll
;     for (int kk = 0; kk < 4; kk++)
; #pragma unroll
;         for (int sub = 0; sub < 2; sub++) {
;             const bf16x8 kf = *(const bf16x8*)(Kl + (sub * 32 + l31) * LROW + kk * 32 + hh * 16);
;             S[sub] = MFMA(kf, qf[kk], S[sub]);
;         }
;     if (domask) {
; #pragma unroll
;         for (int sub = 0; sub < 2; sub++)
; #pragma unroll
;             for (int r = 0; r < 16; r++) {
;                 const int d = qpos - (kpos0 + sub * 32 + (r & 3) + 8 * (r >> 2) + 4 * hh);
;                 S[sub][r] = (d <= 128 && d >= -128) ? S[sub][r] : -1e30f;
;             }
;     }
;     float mx = S[0][0];
; #pragma unroll
;     for (int sub = 0; sub < 2; sub++)
; #pragma unroll
;         for (int r = 0; r < 16; r++) mx = fmaxf(mx, S[sub][r]);
;     mx = fmaxf(mx, __shfl_xor(mx, 32));
;     const float mxs = mx * SL2;
;     if (__any(mxs > m + THR)) {
;         const float mnew = fmaxf(m, mxs);
;         const float alpha = __builtin_amdgcn_exp2f(m - mnew);
;         m = mnew; l *= alpha;
; #pragma unroll
;         for (int dt = 0; dt < DV / 32; dt++)
; #pragma unroll
;             for (int r = 0; r < 16; r++) O[dt][r] *= alpha;
;     }
.LBB0_501:
	s_add_i32 s0, s30, 0
	v_add3_u32 v0, s0, v191, v144
	ds_read_b128 v[2:5], v0 offset:36864
	s_waitcnt lgkmcnt(0)
	v_mfma_f32_32x32x16_bf16 v[96:111], v[2:5], v[124:127], 0
	ds_read_b128 v[2:5], v0 offset:41472
	s_waitcnt lgkmcnt(0)
	v_mfma_f32_32x32x16_bf16 v[80:95], v[2:5], v[124:127], 0
	ds_read_b128 v[2:5], v0 offset:36896
	s_waitcnt lgkmcnt(0)
	v_mfma_f32_32x32x16_bf16 v[96:111], v[2:5], v[120:123], v[96:111]
	ds_read_b128 v[2:5], v0 offset:41504
	s_waitcnt lgkmcnt(0)
	v_mfma_f32_32x32x16_bf16 v[80:95], v[2:5], v[120:123], v[80:95]
	ds_read_b128 v[2:5], v0 offset:36928
	s_waitcnt lgkmcnt(0)
	v_mfma_f32_32x32x16_bf16 v[96:111], v[2:5], v[116:119], v[96:111]
	ds_read_b128 v[2:5], v0 offset:36960
	s_waitcnt lgkmcnt(0)
	v_mfma_f32_32x32x16_bf16 v[96:111], v[2:5], v[112:115], v[96:111]
	ds_read_b128 v[2:5], v0 offset:41536
	ds_read_b128 v[6:9], v0 offset:41568
	s_waitcnt lgkmcnt(1)
	v_mfma_f32_32x32x16_bf16 v[80:95], v[2:5], v[116:119], v[80:95]
	s_nop 7
	v_max_f32_e32 v0, v97, v97
	v_max_f32_e32 v10, v96, v96
	v_max_f32_e32 v0, v10, v0
	v_max3_f32 v0, v0, v98, v99
	v_max3_f32 v0, v0, v100, v101
	v_max3_f32 v0, v0, v102, v103
	v_max3_f32 v0, v0, v104, v105
	s_waitcnt lgkmcnt(0)
	v_mfma_f32_32x32x16_bf16 v[80:95], v[6:9], v[112:115], v[80:95]
	v_max3_f32 v0, v0, v106, v107
	v_max3_f32 v0, v0, v108, v109
	v_max3_f32 v0, v0, v110, v111
	s_nop 8
	v_max3_f32 v0, v0, v80, v81
	v_max3_f32 v0, v0, v82, v83
	v_max3_f32 v0, v0, v84, v85
	v_max3_f32 v0, v0, v86, v87
	v_max3_f32 v0, v0, v88, v89
	v_max3_f32 v0, v0, v90, v91
	v_max3_f32 v0, v0, v92, v93
	v_max3_f32 v0, v0, v94, v95
	ds_bpermute_b32 v2, v192, v0
	s_waitcnt lgkmcnt(0)
	v_max_f32_e32 v2, v2, v2
	v_max_f32_e32 v0, v0, v2
	v_mul_f32_e32 v0, 0x3f800000, v0
	v_add_f32_e32 v2, 0x41000000, v148
	v_cmp_gt_f32_e32 vcc, v0, v2
	s_cbranch_vccz .LBB0_504
	v_max_f32_e64 v0, -v0, -v0
	v_max_f32_e64 v2, -v148, -v148
	v_min_f32_e32 v0, v2, v0
	v_add_f32_e32 v2, v148, v0
	v_exp_f32_e32 v2, v2
	s_nop 0
	v_mul_f32_e32 v145, v145, v2
	v_pk_mul_f32 v[78:79], v[78:79], v[2:3] op_sel_hi:[1,0]
	v_pk_mul_f32 v[76:77], v[76:77], v[2:3] op_sel_hi:[1,0]
	v_pk_mul_f32 v[74:75], v[74:75], v[2:3] op_sel_hi:[1,0]
	v_pk_mul_f32 v[72:73], v[72:73], v[2:3] op_sel_hi:[1,0]
	v_pk_mul_f32 v[70:71], v[70:71], v[2:3] op_sel_hi:[1,0]
	v_pk_mul_f32 v[68:69], v[68:69], v[2:3] op_sel_hi:[1,0]
	v_pk_mul_f32 v[66:67], v[66:67], v[2:3] op_sel_hi:[1,0]
	v_pk_mul_f32 v[64:65], v[64:65], v[2:3] op_sel_hi:[1,0]
	v_pk_mul_f32 v[62:63], v[62:63], v[2:3] op_sel_hi:[1,0]
	v_pk_mul_f32 v[60:61], v[60:61], v[2:3] op_sel_hi:[1,0]
	v_pk_mul_f32 v[58:59], v[58:59], v[2:3] op_sel_hi:[1,0]
	v_pk_mul_f32 v[56:57], v[56:57], v[2:3] op_sel_hi:[1,0]
	v_pk_mul_f32 v[54:55], v[54:55], v[2:3] op_sel_hi:[1,0]
	v_pk_mul_f32 v[52:53], v[52:53], v[2:3] op_sel_hi:[1,0]
	v_pk_mul_f32 v[50:51], v[50:51], v[2:3] op_sel_hi:[1,0]
	v_pk_mul_f32 v[48:49], v[48:49], v[2:3] op_sel_hi:[1,0]
	v_pk_mul_f32 v[46:47], v[46:47], v[2:3] op_sel_hi:[1,0]
	v_pk_mul_f32 v[44:45], v[44:45], v[2:3] op_sel_hi:[1,0]
	v_pk_mul_f32 v[42:43], v[42:43], v[2:3] op_sel_hi:[1,0]
	v_pk_mul_f32 v[40:41], v[40:41], v[2:3] op_sel_hi:[1,0]
	v_pk_mul_f32 v[38:39], v[38:39], v[2:3] op_sel_hi:[1,0]
	v_pk_mul_f32 v[36:37], v[36:37], v[2:3] op_sel_hi:[1,0]
	v_pk_mul_f32 v[34:35], v[34:35], v[2:3] op_sel_hi:[1,0]
	v_pk_mul_f32 v[32:33], v[32:33], v[2:3] op_sel_hi:[1,0]
	v_pk_mul_f32 v[30:31], v[30:31], v[2:3] op_sel_hi:[1,0]
	v_pk_mul_f32 v[28:29], v[28:29], v[2:3] op_sel_hi:[1,0]
	v_pk_mul_f32 v[26:27], v[26:27], v[2:3] op_sel_hi:[1,0]
	v_pk_mul_f32 v[24:25], v[24:25], v[2:3] op_sel_hi:[1,0]
	v_pk_mul_f32 v[22:23], v[22:23], v[2:3] op_sel_hi:[1,0]
	v_pk_mul_f32 v[20:21], v[20:21], v[2:3] op_sel_hi:[1,0]
	v_pk_mul_f32 v[18:19], v[18:19], v[2:3] op_sel_hi:[1,0]
	v_pk_mul_f32 v[16:17], v[16:17], v[2:3] op_sel_hi:[1,0]
	s_branch .LBB0_505

; #define MFMA(a, b, c) __builtin_amdgcn_mfma_f32_32x32x16_bf16((a), (b), (c), 0, 0, 0)
; __device__ __forceinline__ unsigned pk2(float lo, float hi) { const f32x2_t f = {lo, hi}; const bf16x2_t b = __builtin_convertvector(f, bf16x2_t); return __builtin_bit_cast(unsigned, b); }
; template <int DV>
; __device__ __forceinline__ void attn_tile(const unsigned char* Kl, const unsigned char* Vl, const bf16x8 (&qf)[4], f32x16 (&O)[DV / 32], float& m, float& l,
;                                           int l31, int hh, bool domask, int qpos, int kpos0) {
;     ...
;     float ps = 0.f;
; #pragma unroll
;     for (int sub = 0; sub < 2; sub++)
; #pragma unroll
;         for (int r = 0; r < 16; r++) { S[sub][r] = __builtin_amdgcn_exp2f(__builtin_fmaf(S[sub][r], SL2, -m)); ps += S[sub][r]; }
;     l += ps;
;     bf16x8 pb[2][2];
; #pragma unroll
;     for (int sub = 0; sub < 2; sub++)
; #pragma unroll
;         for (int s = 0; s < 2; s++) {
;             u32x4 cv;
;             cv[0] = pk2(S[sub][8 * s + 0], S[sub][8 * s + 1]); cv[1] = pk2(S[sub][8 * s + 2], S[sub][8 * s + 3]);
;             cv[2] = pk2(S[sub][8 * s + 4], S[sub][8 * s + 5]); cv[3] = pk2(S[sub][8 * s + 6], S[sub][8 * s + 7]);
;             pb[sub][s] = __builtin_bit_cast(bf16x8, cv);
;         }
; #pragma unroll
;     for (int sub = 0; sub < 2; sub++)
; #pragma unroll
;         for (int s = 0; s < 2; s++)
; #pragma unroll
;             for (int dt = 0; dt < DV / 32; dt++) {
;                 const bf16x8 vf = *(const bf16x8*)(Vl + (dt * 32 + l31) * LROW + (sub * 4 + s * 2 + hh) * 16);
;                 O[dt] = MFMA(vf, pb[sub][s], O[dt]);
;             }
.LBB0_505:
	v_fmamk_f32 v2, v96, 0x3f800000, v0
	v_exp_f32_e32 v2, v2
	v_fmamk_f32 v4, v97, 0x3f800000, v0
	v_exp_f32_e32 v4, v4
	v_fmamk_f32 v5, v98, 0x3f800000, v0
	v_exp_f32_e32 v5, v5
	v_fmamk_f32 v6, v99, 0x3f800000, v0
	v_exp_f32_e32 v6, v6
	v_fmamk_f32 v7, v100, 0x3f800000, v0
	v_add_f32_e32 v3, 0, v2
	v_exp_f32_e32 v7, v7
	v_fmamk_f32 v8, v101, 0x3f800000, v0
	v_add_f32_e32 v3, v4, v3
	v_exp_f32_e32 v8, v8
	v_fmamk_f32 v9, v102, 0x3f800000, v0
	v_add_f32_e32 v3, v5, v3
	v_exp_f32_e32 v9, v9
	v_fmamk_f32 v10, v103, 0x3f800000, v0
	v_add_f32_e32 v3, v6, v3
	v_exp_f32_e32 v10, v10
	v_fmamk_f32 v11, v104, 0x3f800000, v0
	v_add_f32_e32 v3, v7, v3
	v_exp_f32_e32 v11, v11
	v_fmamk_f32 v12, v105, 0x3f800000, v0
	v_add_f32_e32 v3, v8, v3
	v_exp_f32_e32 v12, v12
	v_fmamk_f32 v13, v106, 0x3f800000, v0
	v_add_f32_e32 v3, v9, v3
	v_exp_f32_e32 v13, v13
	v_fmamk_f32 v14, v107, 0x3f800000, v0
	v_add_f32_e32 v3, v10, v3
	v_exp_f32_e32 v14, v14
	v_fmamk_f32 v15, v108, 0x3f800000, v0
	v_add_f32_e32 v3, v11, v3
	v_exp_f32_e32 v15, v15
	v_fmamk_f32 v96, v109, 0x3f800000, v0
	v_add_f32_e32 v3, v12, v3
	v_exp_f32_e32 v96, v96
	v_fmamk_f32 v97, v110, 0x3f800000, v0
	v_add_f32_e32 v3, v13, v3
	v_exp_f32_e32 v97, v97
	v_fmamk_f32 v98, v111, 0x3f800000, v0
	v_add_f32_e32 v3, v14, v3
	v_exp_f32_e32 v98, v98
	v_fmamk_f32 v80, v80, 0x3f800000, v0
	v_add_f32_e32 v3, v15, v3
	v_exp_f32_e32 v99, v80
	v_fmamk_f32 v80, v81, 0x3f800000, v0
	v_add_f32_e32 v3, v96, v3
	v_exp_f32_e32 v100, v80
	v_fmamk_f32 v80, v82, 0x3f800000, v0
	v_add_f32_e32 v3, v97, v3
	v_exp_f32_e32 v101, v80
	v_fmamk_f32 v80, v83, 0x3f800000, v0
	v_add_f32_e32 v3, v98, v3
	v_exp_f32_e32 v102, v80
	v_fmamk_f32 v80, v84, 0x3f800000, v0
	v_add_f32_e32 v3, v99, v3
	v_exp_f32_e32 v84, v80
	v_fmamk_f32 v80, v85, 0x3f800000, v0
	v_add_f32_e32 v3, v100, v3
	v_exp_f32_e32 v85, v80
	v_fmamk_f32 v80, v86, 0x3f800000, v0
	v_add_f32_e32 v3, v101, v3
	v_exp_f32_e32 v86, v80
	v_fmamk_f32 v80, v87, 0x3f800000, v0
	v_add_f32_e32 v3, v102, v3
	v_exp_f32_e32 v87, v80
	v_fmamk_f32 v80, v88, 0x3f800000, v0
	v_add_f32_e32 v3, v84, v3
	v_exp_f32_e32 v88, v80
	v_fmamk_f32 v80, v89, 0x3f800000, v0
	v_add_f32_e32 v3, v85, v3
	v_exp_f32_e32 v89, v80
	v_fmamk_f32 v80, v90, 0x3f800000, v0
	v_add_f32_e32 v3, v86, v3
	v_exp_f32_e32 v90, v80
	v_fmamk_f32 v80, v91, 0x3f800000, v0
	v_add_f32_e32 v3, v87, v3
	v_exp_f32_e32 v91, v80
	v_fmamk_f32 v80, v92, 0x3f800000, v0
	v_add_f32_e32 v3, v88, v3
	v_exp_f32_e32 v92, v80
	v_fmamk_f32 v80, v93, 0x3f800000, v0
	v_add_f32_e32 v3, v89, v3
	v_exp_f32_e32 v93, v80
	v_fmamk_f32 v80, v94, 0x3f800000, v0
	v_add_f32_e32 v3, v90, v3
	v_exp_f32_e32 v94, v80
	v_fmac_f32_e32 v0, 0x3f800000, v95
	v_add_f32_e32 v3, v91, v3
	v_exp_f32_e32 v95, v0
	v_add_f32_e32 v3, v92, v3
	v_add_f32_e32 v3, v93, v3
	v_add_f32_e32 v3, v94, v3
	v_cvt_pk_bf16_f32 v83, v9, v10
	v_cvt_pk_bf16_f32 v10, v11, v12
	v_cvt_pk_bf16_f32 v11, v13, v14
	v_add3_u32 v14, 0, v191, v144
	v_add_f32_e32 v0, v95, v3
	v_cvt_pk_bf16_f32 v80, v2, v4
	v_cvt_pk_bf16_f32 v82, v7, v8
	v_cvt_pk_bf16_f32 v8, v84, v85
	v_cvt_pk_bf16_f32 v9, v86, v87
	v_cvt_pk_bf16_f32 v2, v88, v89
	v_cvt_pk_bf16_f32 v3, v90, v91
	ds_read_b128 v[84:87], v14 offset:55296
	ds_read_b128 v[88:91], v14 offset:55328
	v_cvt_pk_bf16_f32 v81, v5, v6
	v_cvt_pk_bf16_f32 v12, v15, v96
	v_add_u32_e32 v15, 0xd800, v14
	s_waitcnt lgkmcnt(1)
	v_mfma_f32_32x32x16_bf16 v[64:79], v[84:87], v[80:83], v[64:79]
	ds_read_b128 v[84:87], v14 offset:59904
	v_cvt_pk_bf16_f32 v13, v97, v98
	v_cvt_pk_bf16_f32 v6, v99, v100
	v_cvt_pk_bf16_f32 v7, v101, v102
	v_cvt_pk_bf16_f32 v4, v92, v93
	v_cvt_pk_bf16_f32 v5, v94, v95
	v_add_f32_e32 v0, v145, v0
	s_waitcnt lgkmcnt(0)
	v_mfma_f32_32x32x16_bf16 v[48:63], v[84:87], v[80:83], v[48:63]
	ds_read_b128 v[84:87], v14 offset:64512
	s_waitcnt lgkmcnt(0)
	v_mfma_f32_32x32x16_bf16 v[32:47], v[84:87], v[80:83], v[32:47]
	ds_read_b128 v[84:87], v15 offset:13824
	v_add_u32_e32 v15, 0xd820, v14
	s_waitcnt lgkmcnt(0)
	v_mfma_f32_32x32x16_bf16 v[16:31], v[84:87], v[80:83], v[16:31]
	ds_read_b128 v[80:83], v14 offset:59936
	s_waitcnt lgkmcnt(0)
	v_mfma_f32_32x32x16_bf16 v[48:63], v[80:83], v[10:13], v[48:63]
	ds_read_b128 v[80:83], v14 offset:64544
	s_waitcnt lgkmcnt(0)
	v_mfma_f32_32x32x16_bf16 v[32:47], v[80:83], v[10:13], v[32:47]
	ds_read_b128 v[80:83], v15 offset:13824
	v_add_u32_e32 v15, 0xd840, v14
	v_mfma_f32_32x32x16_bf16 v[64:79], v[88:91], v[10:13], v[64:79]
	s_waitcnt lgkmcnt(0)
	v_mfma_f32_32x32x16_bf16 v[16:31], v[80:83], v[10:13], v[16:31]
	ds_read_b128 v[10:13], v14 offset:55360
	s_waitcnt lgkmcnt(0)
	v_mfma_f32_32x32x16_bf16 v[64:79], v[10:13], v[6:9], v[64:79]
	ds_read_b128 v[10:13], v14 offset:59968
	s_waitcnt lgkmcnt(0)
	v_mfma_f32_32x32x16_bf16 v[48:63], v[10:13], v[6:9], v[48:63]
	ds_read_b128 v[10:13], v14 offset:64576
	s_waitcnt lgkmcnt(0)
	v_mfma_f32_32x32x16_bf16 v[32:47], v[10:13], v[6:9], v[32:47]
	ds_read_b128 v[10:13], v15 offset:13824
	s_waitcnt lgkmcnt(0)
	v_mfma_f32_32x32x16_bf16 v[16:31], v[10:13], v[6:9], v[16:31]
	ds_read_b128 v[6:9], v14 offset:55392
	v_add_u32_e32 v10, 0xd860, v14
	s_waitcnt lgkmcnt(0)
	v_mfma_f32_32x32x16_bf16 v[64:79], v[6:9], v[2:5], v[64:79]
	ds_read_b128 v[6:9], v14 offset:60000
	s_waitcnt lgkmcnt(0)
	v_mfma_f32_32x32x16_bf16 v[48:63], v[6:9], v[2:5], v[48:63]
	ds_read_b128 v[6:9], v14 offset:64608
	s_waitcnt lgkmcnt(0)
	v_mfma_f32_32x32x16_bf16 v[32:47], v[6:9], v[2:5], v[32:47]
	ds_read_b128 v[6:9], v10 offset:13824
	s_waitcnt lgkmcnt(0)
	s_barrier
; template <bool DIFF>
; __device__ __forceinline__ void attn_unit(const Params& p, int layer, int mode, int bl, int hidx, int qblk, bool isctx, unsigned char* lds) {
;     ...
;     float lt = l + __shfl_xor(l, 32);
;     if (DIFF) {
;         const float inv = 1.f / lt;
;         float* xb = (float*)lds + qs * 128 * 32;
;         if (cm == 1) {
; #pragma unroll
;             for (int dt = 0; dt < DV / 32; dt++)
; #pragma unroll
;                 for (int r = 0; r < 16; r++) xb[(dt * 32 + (r & 3) + 8 * (r >> 2) + 4 * hh) * 32 + l31] = O[dt][r] * inv;
;         }
	v_mfma_f32_32x32x16_bf16 v[16:31], v[6:9], v[2:5], v[16:31]
	ds_bpermute_b32 v2, v192, v0
	s_waitcnt lgkmcnt(0)
	v_add_f32_e32 v0, v0, v2
	v_div_scale_f32 v2, s[0:1], v0, v0, 1.0
	v_rcp_f32_e32 v3, v2
	s_lshl_b32 s0, s14, 7
	s_and_b32 s0, s0, 0xffffc000
	s_add_i32 s8, s0, 0
	v_fma_f32 v4, -v2, v3, 1.0
	v_fmac_f32_e32 v3, v4, v3
	v_div_scale_f32 v4, vcc, 1.0, v0, 1.0
	v_mul_f32_e32 v5, v4, v3
	v_fma_f32 v6, -v2, v5, v4
	v_fmac_f32_e32 v5, v6, v3
	v_fma_f32 v2, -v2, v5, v4
	v_div_fmas_f32 v2, v2, v3, v5
	s_cmp_eq_u32 s13, 0
	v_div_fixup_f32 v10, v2, v0, 1.0
	s_cselect_b64 s[0:1], -1, 0
	v_lshlrev_b32_e32 v0, 9, v143
	v_lshlrev_b32_e32 v2, 2, v142
	s_and_b64 vcc, exec, s[0:1]
	v_add3_u32 v0, s8, v0, v2
	s_cbranch_vccnz .LBB0_507
	v_mul_f32_e32 v2, v64, v10
	v_mul_f32_e32 v3, v65, v10
	ds_write2_b32 v0, v2, v3 offset1:32
	v_mul_f32_e32 v2, v66, v10
	v_mul_f32_e32 v3, v67, v10
	ds_write2_b32 v0, v2, v3 offset0:64 offset1:96
	v_mul_f32_e32 v2, v68, v10
	v_mul_f32_e32 v3, v69, v10
	v_add_u32_e32 v4, 0x400, v0
	ds_write2_b32 v4, v2, v3 offset1:32
	v_mul_f32_e32 v2, v70, v10
	v_mul_f32_e32 v3, v71, v10
	ds_write2_b32 v4, v2, v3 offset0:64 offset1:96
	v_mul_f32_e32 v2, v72, v10
	v_mul_f32_e32 v3, v73, v10
	v_add_u32_e32 v4, 0x800, v0
	ds_write2_b32 v4, v2, v3 offset1:32
	v_mul_f32_e32 v2, v74, v10
	v_mul_f32_e32 v3, v75, v10
	ds_write2_b32 v4, v2, v3 offset0:64 offset1:96
	v_mul_f32_e32 v2, v76, v10
	v_mul_f32_e32 v3, v77, v10
	v_add_u32_e32 v4, 0xc00, v0
	ds_write2_b32 v4, v2, v3 offset1:32
	v_mul_f32_e32 v2, v78, v10
	v_mul_f32_e32 v3, v79, v10
	ds_write2_b32 v4, v2, v3 offset0:64 offset1:96
	v_mul_f32_e32 v2, v48, v10
	v_mul_f32_e32 v3, v49, v10
	v_add_u32_e32 v4, 0x1000, v0
	ds_write2_b32 v4, v2, v3 offset1:32
	v_mul_f32_e32 v2, v50, v10
	v_mul_f32_e32 v3, v51, v10
	ds_write2_b32 v4, v2, v3 offset0:64 offset1:96
	v_mul_f32_e32 v2, v52, v10
	v_mul_f32_e32 v3, v53, v10
	v_add_u32_e32 v4, 0x1400, v0
	ds_write2_b32 v4, v2, v3 offset1:32
	v_mul_f32_e32 v2, v54, v10
	v_mul_f32_e32 v3, v55, v10
	ds_write2_b32 v4, v2, v3 offset0:64 offset1:96
	v_mul_f32_e32 v2, v56, v10
	v_mul_f32_e32 v3, v57, v10
	v_add_u32_e32 v4, 0x1800, v0
	ds_write2_b32 v4, v2, v3 offset1:32
	v_mul_f32_e32 v2, v58, v10
	v_mul_f32_e32 v3, v59, v10
	ds_write2_b32 v4, v2, v3 offset0:64 offset1:96
	v_mul_f32_e32 v2, v60, v10
	v_mul_f32_e32 v3, v61, v10
	v_add_u32_e32 v4, 0x1c00, v0
	ds_write2_b32 v4, v2, v3 offset1:32
	v_mul_f32_e32 v2, v62, v10
	v_mul_f32_e32 v3, v63, v10
	ds_write2_b32 v4, v2, v3 offset0:64 offset1:96
	v_mul_f32_e32 v2, v32, v10
	v_mul_f32_e32 v3, v33, v10
	v_add_u32_e32 v4, 0x2000, v0
	ds_write2_b32 v4, v2, v3 offset1:32
	v_mul_f32_e32 v2, v34, v10
	v_mul_f32_e32 v3, v35, v10
	ds_write2_b32 v4, v2, v3 offset0:64 offset1:96
	v_mul_f32_e32 v2, v36, v10
	v_mul_f32_e32 v3, v37, v10
	v_add_u32_e32 v4, 0x2400, v0
	ds_write2_b32 v4, v2, v3 offset1:32
	v_mul_f32_e32 v2, v38, v10
	v_mul_f32_e32 v3, v39, v10
	ds_write2_b32 v4, v2, v3 offset0:64 offset1:96
	v_mul_f32_e32 v2, v40, v10
	v_mul_f32_e32 v3, v41, v10
	v_add_u32_e32 v4, 0x2800, v0
	ds_write2_b32 v4, v2, v3 offset1:32
	v_mul_f32_e32 v2, v42, v10
	v_mul_f32_e32 v3, v43, v10
	ds_write2_b32 v4, v2, v3 offset0:64 offset1:96
	v_mul_f32_e32 v2, v44, v10
	v_mul_f32_e32 v3, v45, v10
	v_add_u32_e32 v4, 0x2c00, v0
	ds_write2_b32 v4, v2, v3 offset1:32
	v_mul_f32_e32 v2, v46, v10
	v_mul_f32_e32 v3, v47, v10
	ds_write2_b32 v4, v2, v3 offset0:64 offset1:96
	v_mul_f32_e32 v2, v16, v10
	v_mul_f32_e32 v3, v17, v10
	v_add_u32_e32 v4, 0x3000, v0
	ds_write2_b32 v4, v2, v3 offset1:32
	v_mul_f32_e32 v2, v18, v10
	v_mul_f32_e32 v3, v19, v10
	ds_write2_b32 v4, v2, v3 offset0:64 offset1:96
	v_mul_f32_e32 v2, v20, v10
	v_mul_f32_e32 v3, v21, v10
	v_add_u32_e32 v4, 0x3400, v0
	ds_write2_b32 v4, v2, v3 offset1:32
	v_mul_f32_e32 v2, v22, v10
	v_mul_f32_e32 v3, v23, v10
	ds_write2_b32 v4, v2, v3 offset0:64 offset1:96
	v_mul_f32_e32 v2, v24, v10
	v_mul_f32_e32 v3, v25, v10
	v_add_u32_e32 v4, 0x3800, v0
	ds_write2_b32 v4, v2, v3 offset1:32
	v_mul_f32_e32 v2, v26, v10
	v_mul_f32_e32 v3, v27, v10
	ds_write2_b32 v4, v2, v3 offset0:64 offset1:96
	v_mul_f32_e32 v2, v28, v10
	v_mul_f32_e32 v3, v29, v10
	v_add_u32_e32 v4, 0x3c00, v0
	ds_write2_b32 v4, v2, v3 offset1:32
	v_mul_f32_e32 v2, v30, v10
	v_mul_f32_e32 v3, v31, v10
	ds_write2_b32 v4, v2, v3 offset0:64 offset1:96

; __global__ void __launch_bounds__(512, 2) fwd_kernel(Params p) {
;     extern __shared__ __attribute__((aligned(16))) unsigned char lds[];
	.amdhsa_kernel _Z10fwd_kernel6Params
		.amdhsa_group_segment_fixed_size 0
		.amdhsa_private_segment_fixed_size 0
		.amdhsa_kernarg_size 456
		.amdhsa_user_sgpr_count 2
		.amdhsa_user_sgpr_dispatch_ptr 0
		.amdhsa_user_sgpr_queue_ptr 0
		.amdhsa_user_sgpr_kernarg_segment_ptr 1
		.amdhsa_user_sgpr_dispatch_id 0
		.amdhsa_user_sgpr_kernarg_preload_length 0
		.amdhsa_user_sgpr_kernarg_preload_offset 0
		.amdhsa_user_sgpr_private_segment_size 0
		.amdhsa_uses_dynamic_stack 0
		.amdhsa_enable_private_segment 0
		.amdhsa_system_sgpr_workgroup_id_x 1
		.amdhsa_system_sgpr_workgroup_id_y 0
		.amdhsa_system_sgpr_workgroup_id_z 0
		.amdhsa_system_sgpr_workgroup_info 0
		.amdhsa_system_vgpr_workitem_id 2
		.amdhsa_next_free_vgpr 255
		.amdhsa_next_free_sgpr 102
		.amdhsa_accum_offset 256
		.amdhsa_reserve_vcc 1
		.amdhsa_float_round_mode_32 0
		.amdhsa_float_round_mode_16_64 0
		.amdhsa_float_denorm_mode_32 3
		.amdhsa_float_denorm_mode_16_64 3
		.amdhsa_dx10_clamp 1
		.amdhsa_ieee_mode 1
		.amdhsa_fp16_overflow 0
		.amdhsa_tg_split 0
		.amdhsa_exception_fp_ieee_invalid_op 0
		.amdhsa_exception_fp_denorm_src 0
		.amdhsa_exception_fp_ieee_div_zero 0
		.amdhsa_exception_fp_ieee_overflow 0
		.amdhsa_exception_fp_ieee_underflow 0
		.amdhsa_exception_fp_ieee_inexact 0
		.amdhsa_exception_int_div_zero 0
	.end_amdhsa_kernel

; __global__ void __launch_bounds__(512, 2) fwd_kernel(Params p) {
;     extern __shared__ __attribute__((aligned(16))) unsigned char lds[];
amdhsa.kernels:
  - .agpr_count:     0
    .args:
      - .offset:         0
        .size:           200
        .value_kind:     by_value
      - .offset:         200
        .size:           4
        .value_kind:     hidden_block_count_x
      - .offset:         204
        .size:           4
        .value_kind:     hidden_block_count_y
      - .offset:         208
        .size:           4
        .value_kind:     hidden_block_count_z
      - .offset:         212
        .size:           2
        .value_kind:     hidden_group_size_x
      - .offset:         214
        .size:           2
        .value_kind:     hidden_group_size_y
      - .offset:         216
        .size:           2
        .value_kind:     hidden_group_size_z
      - .offset:         218
        .size:           2
        .value_kind:     hidden_remainder_x
      - .offset:         220
        .size:           2
        .value_kind:     hidden_remainder_y
      - .offset:         222
        .size:           2
        .value_kind:     hidden_remainder_z
      - .offset:         240
        .size:           8
        .value_kind:     hidden_global_offset_x
      - .offset:         248
        .size:           8
        .value_kind:     hidden_global_offset_y
      - .offset:         256
        .size:           8
        .value_kind:     hidden_global_offset_z
      - .offset:         264
        .size:           2
        .value_kind:     hidden_grid_dims
      - .offset:         288
        .size:           8
        .value_kind:     hidden_multigrid_sync_arg
      - .offset:         320
        .size:           4
        .value_kind:     hidden_dynamic_lds_size
    .group_segment_fixed_size: 0
    .kernarg_segment_align: 8
    .kernarg_segment_size: 456
    .language:       OpenCL C
    .language_version:
      - 2
      - 0
    .max_flat_workgroup_size: 512
    .name:           _Z10fwd_kernel6Params
    .private_segment_fixed_size: 0
    .sgpr_count:     108
    .sgpr_spill_count: 149
    .symbol:         _Z10fwd_kernel6Params.kd
    .uniform_work_group_size: 1
    .uses_dynamic_stack: false
    .vgpr_count:     255
    .vgpr_spill_count: 0
    .wavefront_size: 64
